# v021 + HGRN2 stage B: LDS operand reads of the score / QS.S / state-update MFMA chains software-pipelined over extra register sets v236-v251 (was read-wait-mfma per step)
# speedup vs baseline: 1.0092x; 1.0003x over previous
; #define LAS __attribute__((address_space(3)))
; DI int crow(int i, int hh) { return (i & 3) + 8 * (i >> 2) + 4 * hh; }
; DI s16x4 vtr(const LAS unsigned char* p) { return __builtin_bit_cast(s16x4, __builtin_amdgcn_ds_read_tr16_b64_v4i16((LAS v4i16_t*)p)); }
; DI void hgrn_unit(Ctx A_, LAS unsigned char* lds, int row0, int T, int NC, int h, const float* s0, float* sout, int wave, int lane, int tid) {
;     ...
;         f32x16 X[2];
; #pragma unroll
;         for (int sb = 0; sb < 2; ++sb) {
; #pragma unroll
;             for (int e = 0; e < 16; ++e) X[sb][e] = 0.f;
;             if (sb <= tb) {
; #pragma unroll
;                 for (int d0 = 0; d0 < 8; ++d0) {
;                     const bf16x8 ka = *(const LAS bf16x8*)(lds + OFF_KT + (32 * sb + r) * RP + (16 * d0 + 8 * hh) * 2);
;                     const bf16x8 qb = *(const LAS bf16x8*)(lds + OFF_QT + (32 * tb + r) * RP + (16 * d0 + 8 * hh) * 2);
;                     X[sb] = __builtin_amdgcn_mfma_f32_32x32x16_bf16(ka, qb, X[sb], 0, 0, 0);
;                 }
;                 if (sb == tb) {
; #pragma unroll
;                     for (int e = 0; e < 16; ++e) X[sb][e] = crow(e, hh) > r ? 0.f : X[sb][e];
;                 }
;             }
;         }
;         f32x16 o;
; #pragma unroll
;         for (int e = 0; e < 16; ++e) o[e] = 0.f;
;         { const LAS unsigned char* vp = lds + OFF_V + j * 4096 + g16 * 32 + p4 * 8 + (4 * hh + q4) * 64;
; #pragma unroll
;           for (int sb = 0; sb < 2; ++sb) if (sb <= tb) {
; #pragma unroll
;               for (int s2 = 0; s2 < 2; ++s2) {
;                   const bf16x8 pf = pack8(X[sb], 8 * s2);
;                   const s16x4 lo = vtr(vp + (32 * sb + 16 * s2) * 64), hi = vtr(vp + (32 * sb + 16 * s2) * 64 + 512);
;                   const bf16x8 vf = __builtin_shufflevector(lo, hi, 0, 1, 2, 3, 4, 5, 6, 7);
;                   o = __builtin_amdgcn_mfma_f32_32x32x16_bf16(pf, vf, o, 0, 0, 0);
;               } } }
.LBB0_803:
	s_or_b64 exec, exec, s[54:55]
	v_cndmask_b32_e64 v3, 0, 1, s[96:97]
	v_cmp_ne_u32_e64 s[54:55], 1, v3
	s_andn2_b64 vcc, exec, s[96:97]
	v_add_u32_e32 v3, v195, v194
	v_mov_b32_e32 v83, 0
	v_mov_b32_e32 v84, 0
	v_mov_b32_e32 v85, 0
	v_mov_b32_e32 v86, 0
	v_mov_b32_e32 v87, 0
	v_mov_b32_e32 v88, 0
	v_mov_b32_e32 v89, 0
	v_mov_b32_e32 v90, 0
	v_mov_b32_e32 v91, 0
	v_mov_b32_e32 v92, 0
	v_mov_b32_e32 v93, 0
	v_mov_b32_e32 v94, 0
	v_mov_b32_e32 v95, 0
	v_mov_b32_e32 v96, 0
	v_mov_b32_e32 v97, 0
	s_cbranch_vccnz .LBB0_806
	ds_read_b128 v[4:7], v200 offset:17408
	ds_read_b128 v[8:11], v3
	ds_read_b128 v[236:239], v200 offset:17440
	ds_read_b128 v[240:243], v3 offset:32
	ds_read_b128 v[244:247], v200 offset:17472
	ds_read_b128 v[248:251], v3 offset:64
	s_andn2_b64 vcc, exec, s[36:37]
	s_waitcnt lgkmcnt(4)
	v_mfma_f32_32x32x16_bf16 v[82:97], v[4:7], v[8:11], 0
	ds_read_b128 v[4:7], v200 offset:17504
	ds_read_b128 v[8:11], v3 offset:96
	s_waitcnt lgkmcnt(4)
	v_mfma_f32_32x32x16_bf16 v[82:97], v[236:239], v[240:243], v[82:97]
	ds_read_b128 v[236:239], v200 offset:17536
	ds_read_b128 v[240:243], v3 offset:128
	s_waitcnt lgkmcnt(4)
	v_mfma_f32_32x32x16_bf16 v[82:97], v[244:247], v[248:251], v[82:97]
	ds_read_b128 v[244:247], v200 offset:17568
	ds_read_b128 v[248:251], v3 offset:160
	s_waitcnt lgkmcnt(4)
	v_mfma_f32_32x32x16_bf16 v[82:97], v[4:7], v[8:11], v[82:97]
	ds_read_b128 v[4:7], v200 offset:17600
	ds_read_b128 v[8:11], v3 offset:192
	s_waitcnt lgkmcnt(4)
	v_mfma_f32_32x32x16_bf16 v[82:97], v[236:239], v[240:243], v[82:97]
	ds_read_b128 v[236:239], v200 offset:17632
	ds_read_b128 v[240:243], v3 offset:224
	s_waitcnt lgkmcnt(4)
	v_mfma_f32_32x32x16_bf16 v[82:97], v[244:247], v[248:251], v[82:97]
	s_waitcnt lgkmcnt(2)
	v_mfma_f32_32x32x16_bf16 v[82:97], v[4:7], v[8:11], v[82:97]
	s_waitcnt lgkmcnt(0)
	v_mfma_f32_32x32x16_bf16 v[82:97], v[236:239], v[240:243], v[82:97]
	s_cbranch_vccnz .LBB0_806
	s_nop 10
	v_cndmask_b32_e64 v82, v82, 0, s[20:21]
	v_cndmask_b32_e64 v83, 0, v83, s[22:23]
	v_cndmask_b32_e64 v84, v84, 0, s[24:25]
	v_cndmask_b32_e64 v85, v85, 0, s[26:27]
	v_cndmask_b32_e64 v86, v86, 0, s[28:29]
	v_cndmask_b32_e64 v87, v87, 0, s[30:31]
	v_cndmask_b32_e64 v88, v88, 0, s[34:35]
	v_cndmask_b32_e64 v89, v89, 0, s[92:93]
	v_cndmask_b32_e64 v90, v90, 0, s[86:87]
	v_cndmask_b32_e64 v91, v91, 0, s[64:65]
	v_cndmask_b32_e64 v92, v92, 0, s[66:67]
	v_cndmask_b32_e64 v93, v93, 0, s[68:69]
	v_cndmask_b32_e64 v94, v94, 0, s[70:71]
	v_cndmask_b32_e64 v95, v95, 0, s[80:81]
	v_cndmask_b32_e64 v96, v96, 0, s[82:83]
	v_cndmask_b32_e64 v97, v97, 0, s[52:53]
.LBB0_806:
	v_cndmask_b32_e64 v4, 0, 1, s[84:85]
	v_mov_b32_e32 v114, 0
	v_cmp_ne_u32_e64 s[56:57], 1, v4
	s_andn2_b64 vcc, exec, s[84:85]
	v_mov_b32_e32 v115, 0
	v_mov_b32_e32 v116, 0
	v_mov_b32_e32 v117, 0
	v_mov_b32_e32 v118, 0
	v_mov_b32_e32 v119, 0
	v_mov_b32_e32 v120, 0
	v_mov_b32_e32 v121, 0
	v_mov_b32_e32 v122, 0
	v_mov_b32_e32 v123, 0
	v_mov_b32_e32 v124, 0
	v_mov_b32_e32 v125, 0
	v_mov_b32_e32 v126, 0
	v_mov_b32_e32 v127, 0
	v_mov_b32_e32 v128, 0
	v_mov_b32_e32 v129, 0
	s_cbranch_vccnz .LBB0_809
	ds_read_b128 v[4:7], v201 offset:17408
	ds_read_b128 v[8:11], v3
	ds_read_b128 v[236:239], v201 offset:17440
	ds_read_b128 v[240:243], v3 offset:32
	ds_read_b128 v[244:247], v201 offset:17472
	ds_read_b128 v[248:251], v3 offset:64
	s_andn2_b64 vcc, exec, s[38:39]
	s_waitcnt lgkmcnt(4)
	v_mfma_f32_32x32x16_bf16 v[114:129], v[4:7], v[8:11], 0
	ds_read_b128 v[4:7], v201 offset:17504
	ds_read_b128 v[8:11], v3 offset:96
	s_waitcnt lgkmcnt(4)
	v_mfma_f32_32x32x16_bf16 v[114:129], v[236:239], v[240:243], v[114:129]
	ds_read_b128 v[236:239], v201 offset:17536
	ds_read_b128 v[240:243], v3 offset:128
	s_waitcnt lgkmcnt(4)
	v_mfma_f32_32x32x16_bf16 v[114:129], v[244:247], v[248:251], v[114:129]
	ds_read_b128 v[244:247], v201 offset:17568
	ds_read_b128 v[248:251], v3 offset:160
	s_waitcnt lgkmcnt(4)
	v_mfma_f32_32x32x16_bf16 v[114:129], v[4:7], v[8:11], v[114:129]
	ds_read_b128 v[4:7], v201 offset:17600
	ds_read_b128 v[8:11], v3 offset:192
	s_waitcnt lgkmcnt(4)
	v_mfma_f32_32x32x16_bf16 v[114:129], v[236:239], v[240:243], v[114:129]
	ds_read_b128 v[236:239], v201 offset:17632
	ds_read_b128 v[240:243], v3 offset:224
	s_waitcnt lgkmcnt(4)
	v_mfma_f32_32x32x16_bf16 v[114:129], v[244:247], v[248:251], v[114:129]
	s_waitcnt lgkmcnt(2)
	v_mfma_f32_32x32x16_bf16 v[114:129], v[4:7], v[8:11], v[114:129]
	s_waitcnt lgkmcnt(0)
	v_mfma_f32_32x32x16_bf16 v[114:129], v[236:239], v[240:243], v[114:129]
	s_cbranch_vccnz .LBB0_809
	s_nop 10
	v_cndmask_b32_e64 v114, v114, 0, s[20:21]
	v_cndmask_b32_e64 v115, 0, v115, s[22:23]
	v_cndmask_b32_e64 v116, v116, 0, s[24:25]
	v_cndmask_b32_e64 v117, v117, 0, s[26:27]
	v_cndmask_b32_e64 v118, v118, 0, s[28:29]
	v_cndmask_b32_e64 v119, v119, 0, s[30:31]
	v_cndmask_b32_e64 v120, v120, 0, s[34:35]
	v_cndmask_b32_e64 v121, v121, 0, s[92:93]
	v_cndmask_b32_e64 v122, v122, 0, s[86:87]
	v_cndmask_b32_e64 v123, v123, 0, s[64:65]
	v_cndmask_b32_e64 v124, v124, 0, s[66:67]
	v_cndmask_b32_e64 v125, v125, 0, s[68:69]
	v_cndmask_b32_e64 v126, v126, 0, s[70:71]
	v_cndmask_b32_e64 v127, v127, 0, s[80:81]
	v_cndmask_b32_e64 v128, v128, 0, s[82:83]
	v_cndmask_b32_e64 v129, v129, 0, s[52:53]
.LBB0_809:
	s_and_b64 vcc, exec, s[54:55]
	s_cbranch_vccnz .LBB0_811
	ds_read_b64_tr_b16 v[8:9], v214
	ds_read_b64_tr_b16 v[10:11], v214 offset:512
	ds_read_b64_tr_b16 v[236:237], v214 offset:1024
	ds_read_b64_tr_b16 v[238:239], v214 offset:1536
	v_cvt_pk_bf16_f32 v4, v82, v83
	v_cvt_pk_bf16_f32 v5, v84, v85
	v_cvt_pk_bf16_f32 v6, v86, v87
	v_cvt_pk_bf16_f32 v7, v88, v89
	s_waitcnt lgkmcnt(2)
	s_nop 0
	v_mfma_f32_32x32x16_bf16 v[98:113], v[4:7], v[8:11], 0
	v_cvt_pk_bf16_f32 v4, v90, v91
	v_cvt_pk_bf16_f32 v5, v92, v93
	v_cvt_pk_bf16_f32 v6, v94, v95
	v_cvt_pk_bf16_f32 v7, v96, v97
	s_waitcnt lgkmcnt(0)
	s_nop 0
	v_mfma_f32_32x32x16_bf16 v[98:113], v[4:7], v[236:239], v[98:113]
	s_and_b64 vcc, exec, s[56:57]
	s_cbranch_vccz .LBB0_812
	s_branch .LBB0_813

; #define LAS __attribute__((address_space(3)))
; DI int crow(int i, int hh) { return (i & 3) + 8 * (i >> 2) + 4 * hh; }
; DI s16x4 vtr(const LAS unsigned char* p) { return __builtin_bit_cast(s16x4, __builtin_amdgcn_ds_read_tr16_b64_v4i16((LAS v4i16_t*)p)); }
; DI void hgrn_unit(Ctx A_, LAS unsigned char* lds, int row0, int T, int NC, int h, const float* s0, float* sout, int wave, int lane, int tid) {
;     ...
;           for (int sb = 0; sb < 2; ++sb) if (sb <= tb) {
; #pragma unroll
;               for (int s2 = 0; s2 < 2; ++s2) {
;                   const bf16x8 pf = pack8(X[sb], 8 * s2);
;                   const s16x4 lo = vtr(vp + (32 * sb + 16 * s2) * 64), hi = vtr(vp + (32 * sb + 16 * s2) * 64 + 512);
;                   const bf16x8 vf = __builtin_shufflevector(lo, hi, 0, 1, 2, 3, 4, 5, 6, 7);
;                   o = __builtin_amdgcn_mfma_f32_32x32x16_bf16(pf, vf, o, 0, 0, 0);
;               } } }
; #pragma unroll
;         for (int i = 0; i < 4; ++i)
; #pragma unroll
;             for (int s2 = 0; s2 < 2; ++s2) {
;                 const LAS unsigned char* ap = lds + OFF_QS + (32 * tb + r) * RP + (32 * i + 16 * s2 + 4 * hh) * 2;
;                 const v2u alo = *(const LAS v2u*)ap, ahi = *(const LAS v2u*)(ap + 16);
;                 const v4u a4 = {alo.x, alo.y, ahi.x, ahi.y};
;                 o = __builtin_amdgcn_mfma_f32_32x32x16_bf16(__builtin_bit_cast(bf16x8, a4), pack8(S[i], 8 * s2), o, 0, 0, 0);
;             }
; #pragma unroll
;         for (int e = 0; e < 16; ++e) *(LAS float*)(lds + OFF_OX + ((32 * tb + crow(e, hh)) * 128 + 32 * j + r) * 4) = o[e];
; #pragma unroll
;         for (int i = 0; i < 4; ++i)
; #pragma unroll
;             for (int k4 = 0; k4 < 4; ++k4) { const v4f dq = *(const LAS v4f*)(lds + OFF_DEC + (32 * i + 8 * k4 + 4 * hh) * 4);
;                 S[i][4 * k4] *= dq.x; S[i][4 * k4 + 1] *= dq.y; S[i][4 * k4 + 2] *= dq.z; S[i][4 * k4 + 3] *= dq.w; }
.LBB0_812:
	ds_read_b64_tr_b16 v[8:9], v214 offset:2048
	ds_read_b64_tr_b16 v[10:11], v214 offset:2560
	ds_read_b64_tr_b16 v[236:237], v214 offset:3072
	ds_read_b64_tr_b16 v[238:239], v214 offset:3584
	v_cvt_pk_bf16_f32 v4, v114, v115
	v_cvt_pk_bf16_f32 v5, v116, v117
	v_cvt_pk_bf16_f32 v6, v118, v119
	v_cvt_pk_bf16_f32 v7, v120, v121
	s_waitcnt lgkmcnt(2)
	s_nop 0
	v_mfma_f32_32x32x16_bf16 v[98:113], v[4:7], v[8:11], v[98:113]
	v_cvt_pk_bf16_f32 v4, v122, v123
	v_cvt_pk_bf16_f32 v5, v124, v125
	v_cvt_pk_bf16_f32 v6, v126, v127
	v_cvt_pk_bf16_f32 v7, v128, v129
	s_waitcnt lgkmcnt(0)
	s_nop 0
	v_mfma_f32_32x32x16_bf16 v[98:113], v[4:7], v[236:239], v[98:113]
.LBB0_813:
	v_add_u32_e32 v3, v195, v197
	v_add_u32_e32 v3, 0x8800, v3
	ds_read2_b64 v[4:7], v3 offset1:2
	ds_read2_b64 v[236:239], v3 offset0:4 offset1:6
	ds_read2_b64 v[240:243], v3 offset0:8 offset1:10
	ds_read2_b64 v[244:247], v3 offset0:12 offset1:14
	v_cvt_pk_bf16_f32 v12, v18, v19
	v_cvt_pk_bf16_f32 v13, v20, v21
	v_cvt_pk_bf16_f32 v14, v22, v23
	v_cvt_pk_bf16_f32 v15, v24, v25
	s_waitcnt lgkmcnt(3)
	s_nop 0
	v_mfma_f32_32x32x16_bf16 v[98:113], v[4:7], v[12:15], v[98:113]
	ds_read2_b64 v[4:7], v3 offset0:16 offset1:18
	v_cvt_pk_bf16_f32 v8, v26, v27
	v_cvt_pk_bf16_f32 v9, v28, v29
	v_cvt_pk_bf16_f32 v10, v30, v31
	v_cvt_pk_bf16_f32 v11, v32, v33
	s_waitcnt lgkmcnt(3)
	s_nop 0
	v_mfma_f32_32x32x16_bf16 v[98:113], v[236:239], v[8:11], v[98:113]
	ds_read2_b64 v[236:239], v3 offset0:20 offset1:22
	v_cvt_pk_bf16_f32 v12, v34, v35
	v_cvt_pk_bf16_f32 v13, v36, v37
	v_cvt_pk_bf16_f32 v14, v38, v39
	v_cvt_pk_bf16_f32 v15, v40, v41
	s_waitcnt lgkmcnt(3)
	s_nop 0
	v_mfma_f32_32x32x16_bf16 v[98:113], v[240:243], v[12:15], v[98:113]
	ds_read2_b64 v[240:243], v3 offset0:24 offset1:26
	v_cvt_pk_bf16_f32 v8, v42, v43
	v_cvt_pk_bf16_f32 v9, v44, v45
	v_cvt_pk_bf16_f32 v10, v46, v47
	v_cvt_pk_bf16_f32 v11, v48, v49
	s_waitcnt lgkmcnt(3)
	s_nop 0
	v_mfma_f32_32x32x16_bf16 v[98:113], v[244:247], v[8:11], v[98:113]
	ds_read2_b64 v[244:247], v3 offset0:28 offset1:30
	v_cvt_pk_bf16_f32 v12, v50, v51
	v_cvt_pk_bf16_f32 v13, v52, v53
	v_cvt_pk_bf16_f32 v14, v54, v55
	v_cvt_pk_bf16_f32 v15, v56, v57
	s_waitcnt lgkmcnt(3)
	s_nop 0
	v_mfma_f32_32x32x16_bf16 v[98:113], v[4:7], v[12:15], v[98:113]
	v_cvt_pk_bf16_f32 v8, v58, v59
	v_cvt_pk_bf16_f32 v9, v60, v61
	v_cvt_pk_bf16_f32 v10, v62, v63
	v_cvt_pk_bf16_f32 v11, v64, v65
	s_waitcnt lgkmcnt(2)
	s_nop 0
	v_mfma_f32_32x32x16_bf16 v[98:113], v[236:239], v[8:11], v[98:113]
	v_cvt_pk_bf16_f32 v12, v66, v67
	v_cvt_pk_bf16_f32 v13, v68, v69
	v_cvt_pk_bf16_f32 v14, v70, v71
	v_cvt_pk_bf16_f32 v15, v72, v73
	s_waitcnt lgkmcnt(1)
	s_nop 0
	v_mfma_f32_32x32x16_bf16 v[98:113], v[240:243], v[12:15], v[98:113]
	v_cvt_pk_bf16_f32 v8, v74, v75
	v_cvt_pk_bf16_f32 v9, v76, v77
	v_cvt_pk_bf16_f32 v10, v78, v79
	v_cvt_pk_bf16_f32 v11, v80, v81
	v_add_u32_e32 v3, 0, v194
	v_add_u32_e32 v12, 0x1e040, v3
	s_waitcnt lgkmcnt(0)
	v_mfma_f32_32x32x16_bf16 v[98:113], v[244:247], v[8:11], v[98:113]
	s_nop 11
	ds_write_b32 v215, v98
	ds_write_b32 v216, v99
	ds_write_b32 v217, v100
	ds_write_b32 v218, v101
	ds_write_b32 v219, v102
	ds_write_b32 v220, v103
	ds_write_b32 v221, v104
	ds_write_b32 v222, v105
	ds_write_b32 v223, v106
	ds_write_b32 v224, v107
	ds_write_b32 v225, v108
	ds_write_b32 v226, v109
	ds_write_b32 v227, v110
	ds_write_b32 v228, v111
	ds_write_b32 v229, v112
	ds_write_b32 v230, v113
	v_add_u32_e32 v4, 0x1e000, v3
	v_add_u32_e32 v8, 0x1e020, v3
	ds_read_b128 v[4:7], v4
	ds_read_b128 v[8:11], v8
	ds_read_b128 v[12:15], v12
	v_add_u32_e32 v16, 0x1e060, v3
	ds_read_b128 v[82:85], v16
	s_waitcnt lgkmcnt(3)
	v_pk_mul_f32 v[18:19], v[18:19], v[4:5]
	s_waitcnt lgkmcnt(2)
	v_pk_mul_f32 v[22:23], v[22:23], v[8:9]
	v_add_u32_e32 v4, 0x1e080, v3
	v_add_u32_e32 v8, 0x1e0a0, v3
	v_pk_mul_f32 v[24:25], v[24:25], v[10:11]
	v_pk_mul_f32 v[20:21], v[20:21], v[6:7]
	ds_read_b128 v[4:7], v4
	ds_read_b128 v[8:11], v8
	s_waitcnt lgkmcnt(1)
	v_pk_mul_f32 v[34:35], v[34:35], v[4:5]
	s_waitcnt lgkmcnt(0)
	v_pk_mul_f32 v[38:39], v[38:39], v[8:9]
	v_add_u32_e32 v4, 0x1e100, v3
	v_add_u32_e32 v8, 0x1e120, v3
	v_pk_mul_f32 v[40:41], v[40:41], v[10:11]
	v_pk_mul_f32 v[36:37], v[36:37], v[6:7]
	ds_read_b128 v[4:7], v4
	ds_read_b128 v[8:11], v8
	s_waitcnt lgkmcnt(1)
	v_pk_mul_f32 v[50:51], v[50:51], v[4:5]
	s_waitcnt lgkmcnt(0)
	v_pk_mul_f32 v[54:55], v[54:55], v[8:9]
	v_add_u32_e32 v8, 0x1e1a0, v3
	v_pk_mul_f32 v[56:57], v[56:57], v[10:11]
	ds_read_b128 v[8:11], v8
	v_pk_mul_f32 v[26:27], v[26:27], v[12:13]
	v_add_u32_e32 v12, 0x1e0c0, v3
	v_pk_mul_f32 v[28:29], v[28:29], v[14:15]
	ds_read_b128 v[12:15], v12
	v_add_u32_e32 v16, 0x1e0e0, v3
	v_pk_mul_f32 v[30:31], v[30:31], v[82:83]
	v_pk_mul_f32 v[32:33], v[32:33], v[84:85]
	ds_read_b128 v[82:85], v16
	s_waitcnt lgkmcnt(1)
	v_pk_mul_f32 v[42:43], v[42:43], v[12:13]
	v_add_u32_e32 v12, 0x1e140, v3
	v_pk_mul_f32 v[44:45], v[44:45], v[14:15]
	ds_read_b128 v[12:15], v12
	v_add_u32_e32 v16, 0x1e160, v3
	s_waitcnt lgkmcnt(1)
	v_pk_mul_f32 v[46:47], v[46:47], v[82:83]
	v_pk_mul_f32 v[48:49], v[48:49], v[84:85]
	ds_read_b128 v[82:85], v16
	v_add_u32_e32 v4, 0x1e180, v3
	v_pk_mul_f32 v[52:53], v[52:53], v[6:7]
	ds_read_b128 v[4:7], v4
	s_waitcnt lgkmcnt(2)
	v_pk_mul_f32 v[58:59], v[58:59], v[12:13]
	v_add_u32_e32 v12, 0x1e1c0, v3
	v_add_u32_e32 v3, 0x1e1e0, v3
	v_pk_mul_f32 v[60:61], v[60:61], v[14:15]
	ds_read_b128 v[12:15], v12
	s_waitcnt lgkmcnt(2)
	v_pk_mul_f32 v[62:63], v[62:63], v[82:83]
	v_pk_mul_f32 v[64:65], v[64:65], v[84:85]
	ds_read_b128 v[82:85], v3
	v_add_u32_e32 v3, v196, v199
	v_pk_mul_f32 v[70:71], v[70:71], v[8:9]
	v_pk_mul_f32 v[72:73], v[72:73], v[10:11]
	s_waitcnt lgkmcnt(2)
; #define LAS __attribute__((address_space(3)))
; DI s16x4 vtr(const LAS unsigned char* p) { return __builtin_bit_cast(s16x4, __builtin_amdgcn_ds_read_tr16_b64_v4i16((LAS v4i16_t*)p)); }
; #define HG_LBAR() do { asm volatile("s_waitcnt lgkmcnt(0)" ::: "memory"); __builtin_amdgcn_s_barrier(); asm volatile("" ::: "memory"); } while (0)
; DI void hgrn_unit(Ctx A_, LAS unsigned char* lds, int row0, int T, int NC, int h, const float* s0, float* sout, int wave, int lane, int tid) {
;     ...
; #pragma unroll
;         for (int ks = 0; ks < 4; ++ks) {
;             const LAS unsigned char* vq = lds + OFF_V + j * 4096 + (16 * ks + 8 * hh + q4) * 64 + g16 * 32 + p4 * 8;
;             const s16x4 vlo = vtr(vq), vhi = vtr(vq + 256);
;             const bf16x8 vb = __builtin_shufflevector(vlo, vhi, 0, 1, 2, 3, 4, 5, 6, 7);
; #pragma unroll
;             for (int i = 0; i < 4; ++i) {
;                 const LAS unsigned char* kq = lds + OFF_KS + (16 * ks + 8 * hh + q4) * RP + (32 * i + 16 * g16 + 4 * p4) * 2;
;                 const s16x4 klo = vtr(kq), khi = vtr(kq + 4 * RP);
;                 const bf16x8 ka = __builtin_shufflevector(klo, khi, 0, 1, 2, 3, 4, 5, 6, 7);
;                 S[i] = __builtin_amdgcn_mfma_f32_32x32x16_bf16(ka, vb, S[i], 0, 0, 0);
;             }
;         }
;         HG_LBAR();
;         {
;             const int t = tid >> 3, cg = tid & 7;
;             const LAS v4f* ox = (const LAS v4f*)(lds + OFF_OX + (t * 128 + 16 * cg) * 4);
;             const v4f x0 = ox[0], x1 = ox[1], x2 = ox[2], x3 = ox[3];
;             float ss = (x0.x * x0.x + x0.y * x0.y + x0.z * x0.z + x0.w * x0.w) + (x1.x * x1.x + x1.y * x1.y + x1.z * x1.z + x1.w * x1.w)
;                      + (x2.x * x2.x + x2.y * x2.y + x2.z * x2.z + x2.w * x2.w) + (x3.x * x3.x + x3.y * x3.y + x3.z * x3.z + x3.w * x3.w);
;             ss += __shfl_xor(ss, 1); ss += __shfl_xor(ss, 2); ss += __shfl_xor(ss, 4);
	v_pk_mul_f32 v[68:69], v[68:69], v[6:7]
	v_pk_mul_f32 v[66:67], v[66:67], v[4:5]
	ds_read_b64_tr_b16 v[4:5], v3
	ds_read_b64_tr_b16 v[6:7], v3 offset:256
	ds_read_b64_tr_b16 v[8:9], v202 offset:52224
	ds_read_b64_tr_b16 v[10:11], v202 offset:53312
	ds_read_b64_tr_b16 v[236:237], v202 offset:52288
	ds_read_b64_tr_b16 v[238:239], v202 offset:53376
	ds_read_b64_tr_b16 v[240:241], v202 offset:52352
	ds_read_b64_tr_b16 v[242:243], v202 offset:53440
	ds_read_b64_tr_b16 v[244:245], v202 offset:52416
	ds_read_b64_tr_b16 v[246:247], v202 offset:53504
	ds_read_b64_tr_b16 v[248:249], v203
	ds_read_b64_tr_b16 v[250:251], v203 offset:256
	s_waitcnt lgkmcnt(8)
	v_mfma_f32_32x32x16_bf16 v[18:33], v[8:11], v[4:7], v[18:33]
	v_mul_f32_e64 v78, v78, v82
	v_mul_f32_e64 v79, v79, v83
	v_mul_f32_e64 v74, v74, v12
	v_mul_f32_e64 v75, v75, v13
	v_pk_mul_f32 v[80:81], v[80:81], v[84:85]
	v_pk_mul_f32 v[76:77], v[76:77], v[14:15]
	ds_read_b64_tr_b16 v[8:9], v202 offset:56576
	ds_read_b64_tr_b16 v[10:11], v202 offset:57664
	s_waitcnt lgkmcnt(8)
	v_mfma_f32_32x32x16_bf16 v[34:49], v[236:239], v[4:7], v[34:49]
	ds_read_b64_tr_b16 v[236:237], v202 offset:56640
	ds_read_b64_tr_b16 v[238:239], v202 offset:57728
	s_waitcnt lgkmcnt(8)
	v_mfma_f32_32x32x16_bf16 v[50:65], v[240:243], v[4:7], v[50:65]
	ds_read_b64_tr_b16 v[240:241], v202 offset:56704
	ds_read_b64_tr_b16 v[242:243], v202 offset:57792
	s_waitcnt lgkmcnt(8)
	v_mfma_f32_32x32x16_bf16 v[66:81], v[244:247], v[4:7], v[66:81]
	ds_read_b64_tr_b16 v[244:245], v202 offset:56768
	ds_read_b64_tr_b16 v[246:247], v202 offset:57856
	ds_read_b64_tr_b16 v[4:5], v210
	ds_read_b64_tr_b16 v[6:7], v210 offset:256
	s_waitcnt lgkmcnt(8)
	v_mfma_f32_32x32x16_bf16 v[18:33], v[8:11], v[248:251], v[18:33]
	ds_read_b64_tr_b16 v[8:9], v202 offset:60928
	ds_read_b64_tr_b16 v[10:11], v202 offset:62016
	s_waitcnt lgkmcnt(8)
	v_mfma_f32_32x32x16_bf16 v[34:49], v[236:239], v[248:251], v[34:49]
	ds_read_b64_tr_b16 v[236:237], v202 offset:60992
	ds_read_b64_tr_b16 v[238:239], v202 offset:62080
	s_waitcnt lgkmcnt(8)
	v_mfma_f32_32x32x16_bf16 v[50:65], v[240:243], v[248:251], v[50:65]
	ds_read_b64_tr_b16 v[240:241], v202 offset:61056
	ds_read_b64_tr_b16 v[242:243], v202 offset:62144
	s_waitcnt lgkmcnt(8)
	v_mfma_f32_32x32x16_bf16 v[66:81], v[244:247], v[248:251], v[66:81]
	ds_read_b64_tr_b16 v[244:245], v202 offset:61120
	ds_read_b64_tr_b16 v[246:247], v202 offset:62208
	ds_read_b64_tr_b16 v[248:249], v211
	ds_read_b64_tr_b16 v[250:251], v211 offset:256
	s_waitcnt lgkmcnt(8)
	v_mfma_f32_32x32x16_bf16 v[18:33], v[8:11], v[4:7], v[18:33]
	ds_read_b64_tr_b16 v[8:9], v202 offset:65280
	ds_read_b64_tr_b16 v[10:11], v212 offset:62016
	s_waitcnt lgkmcnt(8)
	v_mfma_f32_32x32x16_bf16 v[34:49], v[236:239], v[4:7], v[34:49]
	ds_read_b64_tr_b16 v[236:237], v202 offset:65344
	ds_read_b64_tr_b16 v[238:239], v212 offset:62080
	s_waitcnt lgkmcnt(8)
	v_mfma_f32_32x32x16_bf16 v[50:65], v[240:243], v[4:7], v[50:65]
	ds_read_b64_tr_b16 v[240:241], v202 offset:65408
	ds_read_b64_tr_b16 v[242:243], v212 offset:62144
	s_waitcnt lgkmcnt(8)
	v_mfma_f32_32x32x16_bf16 v[66:81], v[244:247], v[4:7], v[66:81]
	ds_read_b64_tr_b16 v[244:245], v202 offset:65472
	ds_read_b64_tr_b16 v[246:247], v212 offset:62208
	s_waitcnt lgkmcnt(6)
	v_mfma_f32_32x32x16_bf16 v[18:33], v[8:11], v[248:251], v[18:33]
	s_waitcnt lgkmcnt(4)
	v_mfma_f32_32x32x16_bf16 v[34:49], v[236:239], v[248:251], v[34:49]
	s_waitcnt lgkmcnt(2)
	v_mfma_f32_32x32x16_bf16 v[50:65], v[240:243], v[248:251], v[50:65]
	s_waitcnt lgkmcnt(0)
	s_waitcnt lgkmcnt(0)
	s_barrier
	v_mfma_f32_32x32x16_bf16 v[66:81], v[244:247], v[248:251], v[66:81]
	ds_read_b128 v[82:85], v213
	ds_read_b128 v[12:15], v213 offset:16
	ds_read_b128 v[8:11], v213 offset:32
	ds_read_b128 v[4:7], v213 offset:48
	s_waitcnt lgkmcnt(3)
	v_mul_f32_e32 v3, v83, v83
	s_waitcnt lgkmcnt(2)
	v_mul_f32_e32 v16, v13, v13
	v_fmac_f32_e32 v3, v82, v82
	v_fmac_f32_e32 v16, v12, v12
	v_fmac_f32_e32 v3, v84, v84
	v_fmac_f32_e32 v16, v14, v14
	v_fmac_f32_e32 v3, v85, v85
	v_fmac_f32_e32 v16, v15, v15
	v_add_f32_e32 v3, v3, v16
	s_waitcnt lgkmcnt(1)
	v_mul_f32_e32 v16, v9, v9
	v_fmac_f32_e32 v16, v8, v8
	v_fmac_f32_e32 v16, v10, v10
	v_fmac_f32_e32 v16, v11, v11
	v_add_f32_e32 v3, v3, v16
	s_waitcnt lgkmcnt(0)
	v_mul_f32_e32 v16, v5, v5
	v_fmac_f32_e32 v16, v4, v4
	v_fmac_f32_e32 v16, v6, v6
	v_fmac_f32_e32 v16, v7, v7
	v_add_f32_e32 v3, v3, v16
	s_nop 1
	v_mov_b32_dpp v16, v3 quad_perm:[1,0,3,2] row_mask:0xf bank_mask:0xf
	s_waitcnt lgkmcnt(0)
	v_add_f32_e32 v3, v3, v16
	s_nop 1
	v_mov_b32_dpp v16, v3 quad_perm:[2,3,0,1] row_mask:0xf bank_mask:0xf
	s_waitcnt lgkmcnt(0)
	v_add_f32_e32 v3, v3, v16
	s_nop 1
	v_mov_b32_dpp v16, v3 row_half_mirror row_mask:0xf bank_mask:0xf
	s_and_saveexec_b64 s[56:57], s[18:19]
	s_cbranch_execz .LBB0_776
; DI float bflo(unsigned u) { return __uint_as_float(u << 16); }
; DI float bfhi(unsigned u) { return __uint_as_float(u & 0xffff0000u); }
; DI void hgrn_unit(Ctx A_, LAS unsigned char* lds, int row0, int T, int NC, int h, const float* s0, float* sout, int wave, int lane, int tid) {
;     ...
;             ss += __shfl_xor(ss, 1); ss += __shfl_xor(ss, 2); ss += __shfl_xor(ss, 4);
;             if (t < T) {
;                 const float inv = 1.0f / sqrtf(ss * (1.0f / 128.0f) + NORM_EPS);
;                 const size_t row = (size_t)row0 + 64 * c + t;
;                 const float* gn = HGRN_NORM + h * 128 + 16 * cg;
;                 bf16* yp = Y_ + row * YLD + C_YB + h * 128 + 16 * cg;
;                 const float og[16] = {bflo(ogw0.x), bfhi(ogw0.x), bflo(ogw0.y), bfhi(ogw0.y), bflo(ogw0.z), bfhi(ogw0.z), bflo(ogw0.w), bfhi(ogw0.w), bflo(ogw1.x), bfhi(ogw1.x), bflo(ogw1.y), bfhi(ogw1.y), bflo(ogw1.z), bfhi(ogw1.z), bflo(ogw1.w), bfhi(ogw1.w)};
;                 const float z[16] = {bflo(zw0.x), bfhi(zw0.x), bflo(zw0.y), bfhi(zw0.y), bflo(zw0.z), bfhi(zw0.z), bflo(zw0.w), bfhi(zw0.w), bflo(zw1.x), bfhi(zw1.x), bflo(zw1.y), bfhi(zw1.y), bflo(zw1.z), bfhi(zw1.z), bflo(zw1.w), bfhi(zw1.w)};
;                 const float xv[16] = {x0.x, x0.y, x0.z, x0.w, x1.x, x1.y, x1.z, x1.w, x2.x, x2.y, x2.z, x2.w, x3.x, x3.y, x3.z, x3.w};
;                 float y[16];
; #pragma unroll
;                 for (int e = 0; e < 16; ++e) y[e] = xv[e] * inv * gn[e] * og[e] * z[e];
;                 st8bf(yp, *(float(*)[8])y); st8bf(yp + 8, *(float(*)[8])(y + 8));
;             }
	s_waitcnt lgkmcnt(0)
	v_add_f32_e32 v3, v3, v16
	v_fmamk_f32 v3, v3, 0x3c000000, v184
	s_mov_b32 s54, 0xf800000
	v_cmp_gt_f32_e32 vcc, s54, v3
	v_mul_f32_e32 v16, 0x4f800000, v3
	s_waitcnt vmcnt(3)
	v_lshlrev_b32_e32 v109, 16, v134
	v_cndmask_b32_e32 v3, v3, v16, vcc
	v_sqrt_f32_e32 v16, v3
	s_waitcnt vmcnt(1)
	v_lshlrev_b32_e32 v119, 16, v130
	v_and_b32_e32 v107, 0xffff0000, v134
	v_and_b32_e32 v118, 0xffff0000, v130
	v_add_u32_e32 v17, -1, v16
	v_fma_f32 v86, -v17, v16, v3
	v_cmp_ge_f32_e64 s[54:55], 0, v86
	v_add_u32_e32 v86, 1, v16
	v_lshlrev_b32_e32 v103, 16, v136
	v_cndmask_b32_e64 v17, v16, v17, s[54:55]
	v_fma_f32 v16, -v86, v16, v3
	v_cmp_lt_f32_e64 s[54:55], 0, v16
	v_lshlrev_b32_e32 v105, 16, v135
	v_lshlrev_b32_e32 v112, 16, v132
	v_cndmask_b32_e64 v16, v17, v86, s[54:55]
	v_mul_f32_e32 v17, 0x37800000, v16
	v_cndmask_b32_e32 v16, v16, v17, vcc
	v_cmp_class_f32_e32 vcc, v3, v185
	v_lshlrev_b32_e32 v116, 16, v131
	v_and_b32_e32 v102, 0xffff0000, v136
	v_cndmask_b32_e32 v3, v16, v3, vcc
	v_div_scale_f32 v16, s[54:55], v3, v3, 1.0
	v_rcp_f32_e32 v17, v16
	v_and_b32_e32 v104, 0xffff0000, v135
	v_and_b32_e32 v110, 0xffff0000, v132
	v_and_b32_e32 v114, 0xffff0000, v131
	v_fma_f32 v86, -v16, v17, 1.0
	v_fmac_f32_e32 v17, v86, v17
	v_div_scale_f32 v86, vcc, 1.0, v3, 1.0
	v_mul_f32_e32 v87, v86, v17
	v_fma_f32 v88, -v16, v87, v86
	v_fmac_f32_e32 v87, v88, v17
	v_fma_f32 v16, -v16, v87, v86
	v_div_fmas_f32 v16, v16, v17, v87
	global_load_dwordx4 v[86:89], v[170:171], off offset:48
	global_load_dwordx4 v[90:93], v[170:171], off offset:32
	global_load_dwordx4 v[94:97], v[170:171], off offset:16
	global_load_dwordx4 v[98:101], v[170:171], off
	v_div_fixup_f32 v3, v16, v3, 1.0
	v_mul_f32_e32 v8, v8, v3
	v_mul_f32_e32 v4, v4, v3
	v_mul_f32_e32 v82, v82, v3
	v_mul_f32_e32 v83, v83, v3
	v_mul_f32_e32 v84, v84, v3
	v_mul_f32_e32 v85, v85, v3
	v_mul_f32_e32 v12, v12, v3
	v_mul_f32_e32 v13, v13, v3
	v_mul_f32_e32 v14, v14, v3
	v_mul_f32_e32 v15, v15, v3
	v_lshlrev_b32_e32 v235, 16, v142
	v_and_b32_e32 v127, 0xffff0000, v142
	v_lshlrev_b32_e32 v126, 16, v143
	v_and_b32_e32 v122, 0xffff0000, v143
	v_lshlrev_b32_e32 v117, 16, v144
	v_and_b32_e32 v115, 0xffff0000, v144
	v_lshlrev_b32_e32 v113, 16, v145
	v_and_b32_e32 v111, 0xffff0000, v145
	v_lshlrev_b32_e32 v17, 16, v137
	v_and_b32_e32 v16, 0xffff0000, v137
	s_waitcnt vmcnt(4)
	v_lshlrev_b32_e32 v134, 16, v138
	v_and_b32_e32 v129, 0xffff0000, v138
	v_lshlrev_b32_e32 v128, 16, v139
	v_and_b32_e32 v125, 0xffff0000, v139
	v_lshlrev_b32_e32 v124, 16, v140
	v_and_b32_e32 v123, 0xffff0000, v140
	v_lshlrev_b32_e32 v121, 16, v141
	v_and_b32_e32 v120, 0xffff0000, v141
	v_lshlrev_b32_e32 v108, 16, v133
	v_and_b32_e32 v106, 0xffff0000, v133
	s_waitcnt vmcnt(3)
	v_mul_f32_e32 v4, v4, v86
	s_waitcnt vmcnt(2)
	v_mul_f32_e32 v8, v8, v90
	v_mul_f32_e32 v8, v8, v109
	v_mul_f32_e32 v90, v8, v119
	v_mul_f32_e32 v8, v9, v3
	v_mul_f32_e32 v8, v8, v91
	v_mul_f32_e32 v8, v8, v107
	v_mul_f32_e32 v91, v8, v118
	v_mul_f32_e32 v8, v10, v3
	v_mul_f32_e32 v8, v8, v92
	v_mul_f32_e32 v4, v4, v103
	v_mul_f32_e32 v8, v8, v105
	v_mul_f32_e32 v86, v4, v112
	v_mul_f32_e32 v4, v5, v3
	v_mul_f32_e32 v10, v8, v116
	v_mul_f32_e32 v8, v11, v3
	v_mul_f32_e32 v4, v4, v87
	v_mul_f32_e32 v8, v8, v93
	v_mul_f32_e32 v4, v4, v102
	v_mul_f32_e32 v8, v8, v104
	v_mul_f32_e32 v87, v4, v110
	v_mul_f32_e32 v4, v6, v3
	s_waitcnt vmcnt(0)
	v_mul_f32_e32 v82, v82, v98
	v_mul_f32_e32 v83, v83, v99
	v_mul_f32_e32 v84, v84, v100
	v_mul_f32_e32 v85, v85, v101
	v_mul_f32_e32 v12, v12, v94
	v_mul_f32_e32 v13, v13, v95
	v_mul_f32_e32 v14, v14, v96
	v_mul_f32_e32 v15, v15, v97
	v_mul_f32_e32 v11, v8, v114
	v_mul_f32_e32 v4, v4, v88
	v_mul_f32_e32 v3, v7, v3
	v_lshl_add_u64 v[8:9], s[50:51], 0, v[176:177]
	v_mul_f32_e32 v82, v82, v235
	v_mul_f32_e32 v83, v83, v127
	v_mul_f32_e32 v84, v84, v126
	v_mul_f32_e32 v85, v85, v122
	v_mul_f32_e32 v12, v12, v117
	v_mul_f32_e32 v13, v13, v115
	v_mul_f32_e32 v14, v14, v113
	v_mul_f32_e32 v15, v15, v111
	v_mul_f32_e32 v4, v4, v17
	v_mul_f32_e32 v3, v3, v89
	v_add_co_u32_e32 v8, vcc, 0x64900000, v8
	v_mul_f32_e32 v82, v82, v134
	v_mul_f32_e32 v83, v83, v129
	v_mul_f32_e32 v84, v84, v128
	v_mul_f32_e32 v85, v85, v125
	v_mul_f32_e32 v12, v12, v124
	v_mul_f32_e32 v13, v13, v123
	v_mul_f32_e32 v14, v14, v121
	v_mul_f32_e32 v15, v15, v120
	v_mul_f32_e32 v17, v4, v108
	v_mul_f32_e32 v3, v3, v16
	v_cvt_pk_bf16_f32 v4, v82, v83
	v_cvt_pk_bf16_f32 v5, v84, v85
	v_cvt_pk_bf16_f32 v6, v12, v13
	v_cvt_pk_bf16_f32 v7, v14, v15
	v_addc_co_u32_e32 v9, vcc, 0, v9, vcc
	v_mul_f32_e32 v3, v3, v106
	global_store_dwordx4 v[8:9], v[4:7], off offset:2048
	s_nop 1
	v_cvt_pk_bf16_f32 v4, v90, v91
	v_cvt_pk_bf16_f32 v5, v10, v11
	v_cvt_pk_bf16_f32 v6, v86, v87
	v_cvt_pk_bf16_f32 v7, v17, v3
	global_store_dwordx4 v[8:9], v[4:7], off offset:2064
	s_branch .LBB0_776
